# wave-priority bias toward the critical RG-LRU half (s_setprio 2 for RG-LRU loop, 1 elsewhere) on top of v145
# baseline (speedup 1.0000x reference)
; __device__ __forceinline__ void rglru_unit(const Params& p, const WS& ws, int j, int u, bool dry = false) {
;     ...
;   float ba[2][4], bx[2][4], sp[2][4];
; #pragma unroll
;   for (int mt = 0; mt < 2; ++mt)
; #pragma unroll
;     for (int jj = 0; jj < 4; ++jj) {
;       const int ch = j * 1024 + 128 * g + 32 * jq + 16 * mt + 4 * lq + jj;
;       ba[mt][jj] = p.ab_gate_a_b[ch]; bx[mt][jj] = p.ab_gate_x_b[ch];
;       sp[mt][jj] = 8.f * log1pf(__expf(-p.ab_lam[ch]));
;     }
.LBB0_1375:
	s_or_b64 exec, exec, s[6:7]
	s_waitcnt vmcnt(1)
	v_mul_f32_e32 v13, 0xbfb8aa3b, v56
	v_exp_f32_e32 v13, v13
	s_mov_b32 s3, 0x3f2aaaab
	s_mov_b32 s10, 0x3f317218
	s_mov_b32 s11, 0x33800000
	v_add_f32_e32 v15, 1.0, v13
	v_add_f32_e32 v56, -1.0, v15
	v_sub_f32_e32 v67, v56, v15
	v_frexp_mant_f32_e32 v63, v15
	v_cvt_f64_f32_e32 v[70:71], v15
	v_sub_f32_e32 v56, v13, v56
	v_add_f32_e32 v67, 1.0, v67
	v_add_f32_e32 v56, v56, v67
	v_frexp_exp_i32_f64_e32 v67, v[70:71]
	v_cmp_gt_f32_e32 vcc, s3, v63
	s_lshl_b32 s92, s9, 1
	s_movk_i32 s9, 0x84
	v_subbrev_co_u32_e32 v63, vcc, 0, v67, vcc
	v_sub_u32_e32 v67, 0, v63
	v_ldexp_f32 v15, v15, v67
	v_ldexp_f32 v56, v56, v67
	v_add_f32_e32 v67, -1.0, v15
	v_add_f32_e32 v71, 1.0, v15
	v_add_f32_e32 v69, 1.0, v67
	v_add_f32_e32 v72, -1.0, v71
	v_sub_f32_e32 v69, v15, v69
	v_sub_f32_e32 v15, v15, v72
	v_add_f32_e32 v15, v56, v15
	v_add_f32_e32 v69, v56, v69
	v_add_f32_e32 v56, v71, v15
	v_rcp_f32_e32 v72, v56
	v_add_f32_e32 v70, v67, v69
	v_sub_f32_e32 v67, v70, v67
	v_sub_f32_e32 v67, v69, v67
	v_sub_f32_e32 v69, v56, v71
	v_sub_f32_e32 v15, v15, v69
	v_mul_f32_e32 v69, v70, v72
	v_mul_f32_e32 v71, v56, v69
	v_fma_f32 v73, v69, v56, -v71
	v_fmac_f32_e32 v73, v69, v15
	v_add_f32_e32 v74, v71, v73
	v_sub_f32_e32 v75, v70, v74
	v_sub_f32_e32 v70, v70, v75
	v_sub_f32_e32 v71, v74, v71
	v_sub_f32_e32 v70, v70, v74
	v_add_f32_e32 v67, v67, v70
	v_sub_f32_e32 v70, v71, v73
	v_add_f32_e32 v67, v70, v67
	v_add_f32_e32 v70, v75, v67
	v_mul_f32_e32 v71, v72, v70
	v_mul_f32_e32 v73, v56, v71
	v_fma_f32 v56, v71, v56, -v73
	v_fmac_f32_e32 v56, v71, v15
	v_sub_f32_e32 v15, v75, v70
	v_add_f32_e32 v15, v67, v15
	v_add_f32_e32 v67, v73, v56
	v_sub_f32_e32 v74, v70, v67
	v_sub_f32_e32 v70, v70, v74
	v_sub_f32_e32 v73, v67, v73
	v_sub_f32_e32 v67, v70, v67
	v_add_f32_e32 v15, v15, v67
	v_sub_f32_e32 v56, v73, v56
	v_cvt_f32_i32_e32 v63, v63
	v_add_f32_e32 v15, v56, v15
	v_add_f32_e32 v56, v69, v71
	v_add_f32_e32 v15, v74, v15
	v_sub_f32_e32 v67, v56, v69
	v_mul_f32_e32 v15, v72, v15
	v_sub_f32_e32 v67, v71, v67
	v_add_f32_e32 v15, v67, v15
	v_mul_f32_e32 v71, 0x3f317218, v63
	v_add_f32_e32 v67, v56, v15
	v_fma_f32 v72, v63, s10, -v71
	v_mul_f32_e32 v69, v67, v67
	v_fmac_f32_e32 v72, 0xb102e308, v63
	v_sub_f32_e32 v56, v67, v56
	v_fmamk_f32 v70, v69, 0x3e9b6dac, v192
	v_sub_f32_e32 v15, v15, v56
	v_add_f32_e32 v56, v71, v72
	v_fmaak_f32 v70, v69, v70, 0x3f2aaada
	v_sub_f32_e32 v63, v56, v71
	v_ldexp_f32 v71, v67, 1
	v_mul_f32_e32 v67, v67, v69
	v_mul_f32_e32 v67, v67, v70
	v_add_f32_e32 v69, v71, v67
	v_sub_f32_e32 v70, v69, v71
	v_ldexp_f32 v15, v15, 1
	v_sub_f32_e32 v67, v67, v70
	v_add_f32_e32 v15, v15, v67
	v_add_f32_e32 v67, v69, v15
	v_sub_f32_e32 v69, v67, v69
	v_sub_f32_e32 v15, v15, v69
	v_add_f32_e32 v69, v56, v67
	v_sub_f32_e32 v70, v69, v56
	v_sub_f32_e32 v71, v69, v70
	v_sub_f32_e32 v63, v72, v63
	v_sub_f32_e32 v56, v56, v71
	v_sub_f32_e32 v67, v67, v70
	v_add_f32_e32 v56, v67, v56
	v_add_f32_e32 v67, v63, v15
	v_sub_f32_e32 v70, v67, v63
	v_sub_f32_e32 v71, v67, v70
	v_sub_f32_e32 v63, v63, v71
	v_sub_f32_e32 v15, v15, v70
	v_add_f32_e32 v56, v67, v56
	v_add_f32_e32 v15, v15, v63
	v_add_f32_e32 v63, v69, v56
	v_sub_f32_e32 v67, v63, v69
	v_sub_f32_e32 v56, v56, v67
	v_add_f32_e32 v15, v15, v56
	v_add_f32_e32 v15, v63, v15
	v_cmp_neq_f32_e32 vcc, s21, v13
	v_mul_f32_e32 v56, 0xbfb8aa3b, v57
	v_exp_f32_e32 v63, v56
	v_cndmask_b32_e32 v15, v199, v15, vcc
	v_cmp_ngt_f32_e32 vcc, -1.0, v13
	s_mov_b32 s6, 0
	s_mov_b32 s7, 1
	v_cndmask_b32_e32 v15, v200, v15, vcc
	v_cmp_neq_f32_e32 vcc, -1.0, v13
	v_lshl_add_u32 v115, v60, 2, s8
	v_cmp_lt_i32_e64 s[38:39], 1, v66
	v_cndmask_b32_e32 v15, v194, v15, vcc
	v_cmp_lt_f32_e64 vcc, |v13|, s11
	v_cmp_lt_i32_e64 s[40:41], 2, v66
	v_cmp_lt_i32_e64 s[42:43], 3, v66
	v_cndmask_b32_e32 v13, v15, v13, vcc
	v_mul_f32_e32 v89, 0x41000000, v13
	v_add_f32_e32 v13, 1.0, v63
	v_add_f32_e32 v15, -1.0, v13
	v_sub_f32_e32 v56, v15, v13
	v_add_f32_e32 v56, 1.0, v56
	v_sub_f32_e32 v15, v63, v15
	v_add_f32_e32 v15, v15, v56
	v_frexp_mant_f32_e32 v67, v13
	v_cvt_f64_f32_e32 v[56:57], v13
	v_frexp_exp_i32_f64_e32 v56, v[56:57]
	v_cmp_gt_f32_e32 vcc, s3, v67
	v_cmp_lt_i32_e64 s[44:45], 4, v66
	v_cmp_lt_i32_e64 s[46:47], 5, v66
	v_subbrev_co_u32_e32 v56, vcc, 0, v56, vcc
	v_sub_u32_e32 v57, 0, v56
	v_ldexp_f32 v13, v13, v57
	v_ldexp_f32 v15, v15, v57
	v_add_f32_e32 v57, -1.0, v13
	v_add_f32_e32 v70, 1.0, v13
	v_add_f32_e32 v67, 1.0, v57
	v_add_f32_e32 v71, -1.0, v70
	v_sub_f32_e32 v67, v13, v67
	v_sub_f32_e32 v13, v13, v71
	v_add_f32_e32 v13, v15, v13
	v_add_f32_e32 v67, v15, v67
	v_add_f32_e32 v15, v70, v13
	v_rcp_f32_e32 v71, v15
	v_add_f32_e32 v69, v57, v67
	v_sub_f32_e32 v57, v69, v57
	v_sub_f32_e32 v57, v67, v57
	v_sub_f32_e32 v67, v15, v70
	v_sub_f32_e32 v13, v13, v67
	v_mul_f32_e32 v67, v69, v71
	v_mul_f32_e32 v70, v15, v67
	v_fma_f32 v72, v67, v15, -v70
	v_fmac_f32_e32 v72, v67, v13
	v_add_f32_e32 v73, v70, v72
	v_sub_f32_e32 v74, v69, v73
	v_sub_f32_e32 v69, v69, v74
	v_sub_f32_e32 v70, v73, v70
	v_sub_f32_e32 v69, v69, v73
	v_add_f32_e32 v57, v57, v69
	v_sub_f32_e32 v69, v70, v72
	v_add_f32_e32 v57, v69, v57
	v_add_f32_e32 v69, v74, v57
	v_mul_f32_e32 v70, v71, v69
	v_mul_f32_e32 v72, v15, v70
	v_fma_f32 v15, v70, v15, -v72
	v_fmac_f32_e32 v15, v70, v13
	v_sub_f32_e32 v13, v74, v69
	v_add_f32_e32 v13, v57, v13
	v_add_f32_e32 v57, v72, v15
	v_sub_f32_e32 v73, v69, v57
	v_sub_f32_e32 v69, v69, v73
	v_sub_f32_e32 v72, v57, v72
	v_sub_f32_e32 v57, v69, v57
	v_add_f32_e32 v13, v13, v57
	v_sub_f32_e32 v15, v72, v15
	v_cvt_f32_i32_e32 v56, v56
	v_add_f32_e32 v13, v15, v13
; __device__ __forceinline__ void rglru_unit(const Params& p, const WS& ws, int j, int u, bool dry = false) {
;     ...
;       const int ch = j * 1024 + 128 * g + 32 * jq + 16 * mt + 4 * lq + jj;
;       ba[mt][jj] = p.ab_gate_a_b[ch]; bx[mt][jj] = p.ab_gate_x_b[ch];
;       sp[mt][jj] = 8.f * log1pf(__expf(-p.ab_lam[ch]));
;     }
	v_add_f32_e32 v15, v67, v70
	v_add_f32_e32 v13, v73, v13
	v_sub_f32_e32 v57, v15, v67
	v_mul_f32_e32 v13, v71, v13
	v_sub_f32_e32 v57, v70, v57
	v_add_f32_e32 v13, v57, v13
	v_mul_f32_e32 v70, 0x3f317218, v56
	v_add_f32_e32 v57, v15, v13
	v_fma_f32 v71, v56, s10, -v70
	v_mul_f32_e32 v67, v57, v57
	v_fmac_f32_e32 v71, 0xb102e308, v56
	v_sub_f32_e32 v15, v57, v15
	v_fmamk_f32 v69, v67, 0x3e9b6dac, v192
	v_sub_f32_e32 v13, v13, v15
	v_add_f32_e32 v15, v70, v71
	v_fmaak_f32 v69, v67, v69, 0x3f2aaada
	v_sub_f32_e32 v56, v15, v70
	v_ldexp_f32 v70, v57, 1
	v_mul_f32_e32 v57, v57, v67
	v_mul_f32_e32 v57, v57, v69
	v_add_f32_e32 v67, v70, v57
	v_sub_f32_e32 v69, v67, v70
	v_ldexp_f32 v13, v13, 1
	v_sub_f32_e32 v57, v57, v69
	v_add_f32_e32 v13, v13, v57
	v_add_f32_e32 v57, v67, v13
	v_sub_f32_e32 v67, v57, v67
	v_sub_f32_e32 v13, v13, v67
	v_add_f32_e32 v67, v15, v57
	v_sub_f32_e32 v69, v67, v15
	v_sub_f32_e32 v70, v67, v69
	v_sub_f32_e32 v56, v71, v56
	v_sub_f32_e32 v15, v15, v70
	v_sub_f32_e32 v57, v57, v69
	v_add_f32_e32 v15, v57, v15
	v_add_f32_e32 v57, v56, v13
	v_sub_f32_e32 v69, v57, v56
	v_sub_f32_e32 v70, v57, v69
	v_sub_f32_e32 v56, v56, v70
	v_sub_f32_e32 v13, v13, v69
	v_add_f32_e32 v15, v57, v15
	v_add_f32_e32 v13, v13, v56
	v_add_f32_e32 v56, v67, v15
	v_sub_f32_e32 v57, v56, v67
	v_sub_f32_e32 v15, v15, v57
	v_add_f32_e32 v13, v13, v15
	v_add_f32_e32 v13, v56, v13
	v_cmp_neq_f32_e32 vcc, s21, v63
	v_mul_f32_e32 v15, 0xbfb8aa3b, v58
	v_exp_f32_e32 v15, v15
	v_cndmask_b32_e32 v13, v199, v13, vcc
	v_cmp_ngt_f32_e32 vcc, -1.0, v63
	v_cmp_lt_i32_e64 s[48:49], 6, v66
	v_cmp_eq_u32_e64 s[50:51], 7, v66
	v_cndmask_b32_e32 v13, v200, v13, vcc
	v_cmp_neq_f32_e32 vcc, -1.0, v63
	v_or_b32_e32 v108, 1, v84
	v_or_b32_e32 v104, 2, v84
	v_cndmask_b32_e32 v13, v194, v13, vcc
	v_cmp_lt_f32_e64 vcc, |v63|, s11
	v_or_b32_e32 v103, 3, v84
	v_or_b32_e32 v102, 4, v84
	v_cndmask_b32_e32 v13, v13, v63, vcc
	v_mul_f32_e32 v93, 0x41000000, v13
	v_add_f32_e32 v13, 1.0, v15
	v_add_f32_e32 v56, -1.0, v13
	v_sub_f32_e32 v57, v56, v13
	v_add_f32_e32 v57, 1.0, v57
	v_sub_f32_e32 v56, v15, v56
	v_add_f32_e32 v58, v56, v57
	v_frexp_mant_f32_e32 v63, v13
	v_cvt_f64_f32_e32 v[56:57], v13
	v_frexp_exp_i32_f64_e32 v56, v[56:57]
	v_cmp_gt_f32_e32 vcc, s3, v63
	v_or_b32_e32 v101, 5, v84
	v_or_b32_e32 v100, 6, v84
	v_subbrev_co_u32_e32 v56, vcc, 0, v56, vcc
	v_sub_u32_e32 v57, 0, v56
	v_ldexp_f32 v13, v13, v57
	v_ldexp_f32 v57, v58, v57
	v_add_f32_e32 v58, -1.0, v13
	v_add_f32_e32 v69, 1.0, v13
	v_add_f32_e32 v63, 1.0, v58
	v_add_f32_e32 v70, -1.0, v69
	v_sub_f32_e32 v63, v13, v63
	v_sub_f32_e32 v13, v13, v70
	v_add_f32_e32 v13, v57, v13
	v_add_f32_e32 v63, v57, v63
	v_add_f32_e32 v57, v69, v13
	v_rcp_f32_e32 v70, v57
	v_add_f32_e32 v67, v58, v63
	v_sub_f32_e32 v58, v67, v58
	v_sub_f32_e32 v58, v63, v58
	v_sub_f32_e32 v63, v57, v69
	v_sub_f32_e32 v13, v13, v63
	v_mul_f32_e32 v63, v67, v70
	v_mul_f32_e32 v69, v57, v63
	v_fma_f32 v71, v63, v57, -v69
	v_fmac_f32_e32 v71, v63, v13
	v_add_f32_e32 v72, v69, v71
	v_sub_f32_e32 v73, v67, v72
	v_sub_f32_e32 v67, v67, v73
	v_sub_f32_e32 v69, v72, v69
	v_sub_f32_e32 v67, v67, v72
	v_add_f32_e32 v58, v58, v67
	v_sub_f32_e32 v67, v69, v71
	v_add_f32_e32 v58, v67, v58
	v_add_f32_e32 v67, v73, v58
	v_mul_f32_e32 v69, v70, v67
	v_mul_f32_e32 v71, v57, v69
	v_fma_f32 v57, v69, v57, -v71
	v_fmac_f32_e32 v57, v69, v13
	v_sub_f32_e32 v13, v73, v67
	v_add_f32_e32 v13, v58, v13
	v_add_f32_e32 v58, v71, v57
	v_sub_f32_e32 v72, v67, v58
	v_sub_f32_e32 v67, v67, v72
	v_sub_f32_e32 v71, v58, v71
	v_sub_f32_e32 v58, v67, v58
	v_add_f32_e32 v13, v13, v58
	v_sub_f32_e32 v57, v71, v57
	v_cvt_f32_i32_e32 v56, v56
	v_add_f32_e32 v13, v57, v13
	v_add_f32_e32 v57, v63, v69
	v_add_f32_e32 v13, v72, v13
	v_sub_f32_e32 v58, v57, v63
	v_mul_f32_e32 v13, v70, v13
	v_sub_f32_e32 v58, v69, v58
	v_add_f32_e32 v13, v58, v13
	v_mul_f32_e32 v69, 0x3f317218, v56
	v_add_f32_e32 v58, v57, v13
	v_fma_f32 v70, v56, s10, -v69
	v_mul_f32_e32 v63, v58, v58
	v_fmac_f32_e32 v70, 0xb102e308, v56
	v_sub_f32_e32 v56, v58, v57
	v_fmamk_f32 v67, v63, 0x3e9b6dac, v192
	v_sub_f32_e32 v13, v13, v56
	v_add_f32_e32 v56, v69, v70
	v_fmaak_f32 v67, v63, v67, 0x3f2aaada
	v_sub_f32_e32 v57, v56, v69
	v_ldexp_f32 v69, v58, 1
	v_mul_f32_e32 v58, v58, v63
	v_mul_f32_e32 v58, v58, v67
	v_add_f32_e32 v63, v69, v58
	v_sub_f32_e32 v67, v63, v69
	v_ldexp_f32 v13, v13, 1
	v_sub_f32_e32 v58, v58, v67
	v_add_f32_e32 v13, v13, v58
	v_add_f32_e32 v58, v63, v13
	v_sub_f32_e32 v63, v58, v63
	v_sub_f32_e32 v13, v13, v63
	v_add_f32_e32 v63, v56, v58
	v_sub_f32_e32 v67, v63, v56
	v_sub_f32_e32 v69, v63, v67
	v_sub_f32_e32 v57, v70, v57
	v_sub_f32_e32 v56, v56, v69
	v_sub_f32_e32 v58, v58, v67
	v_add_f32_e32 v56, v58, v56
	v_add_f32_e32 v58, v57, v13
	v_sub_f32_e32 v67, v58, v57
	v_sub_f32_e32 v69, v58, v67
	v_sub_f32_e32 v57, v57, v69
	v_sub_f32_e32 v13, v13, v67
	v_add_f32_e32 v56, v58, v56
	v_add_f32_e32 v13, v13, v57
	v_add_f32_e32 v57, v63, v56
	v_sub_f32_e32 v58, v57, v63
	v_sub_f32_e32 v56, v56, v58
	v_add_f32_e32 v13, v13, v56
	v_add_f32_e32 v13, v57, v13
	v_cmp_neq_f32_e32 vcc, s21, v15
	v_mul_f32_e32 v56, 0xbfb8aa3b, v59
	v_exp_f32_e32 v58, v56
	v_cndmask_b32_e32 v13, v199, v13, vcc
	v_cmp_ngt_f32_e32 vcc, -1.0, v15
	v_add_u32_e32 v116, v81, v84
	v_add_u32_e32 v117, v80, v84
	v_cndmask_b32_e32 v13, v200, v13, vcc
	v_cmp_neq_f32_e32 vcc, -1.0, v15
	v_add_u32_e32 v118, v79, v84
	s_mov_b32 s12, 0
	v_cndmask_b32_e32 v13, v194, v13, vcc
	v_cmp_lt_f32_e64 vcc, |v15|, s11
	s_barrier
; __device__ __forceinline__ void rglru_unit(const Params& p, const WS& ws, int j, int u, bool dry = false) {
;     ...
;       const int ch = j * 1024 + 128 * g + 32 * jq + 16 * mt + 4 * lq + jj;
;       ba[mt][jj] = p.ab_gate_a_b[ch]; bx[mt][jj] = p.ab_gate_x_b[ch];
;       sp[mt][jj] = 8.f * log1pf(__expf(-p.ab_lam[ch]));
;     }
	s_nop 0
	v_cndmask_b32_e32 v13, v13, v15, vcc
	v_mul_f32_e32 v95, 0x41000000, v13
	v_add_f32_e32 v13, 1.0, v58
	v_add_f32_e32 v15, -1.0, v13
	v_sub_f32_e32 v56, v15, v13
	v_add_f32_e32 v56, 1.0, v56
	v_sub_f32_e32 v15, v58, v15
	v_add_f32_e32 v15, v15, v56
	v_frexp_mant_f32_e32 v59, v13
	v_cvt_f64_f32_e32 v[56:57], v13
	v_frexp_exp_i32_f64_e32 v56, v[56:57]
	v_cmp_gt_f32_e32 vcc, s3, v59
	s_nop 1
	v_subbrev_co_u32_e32 v56, vcc, 0, v56, vcc
	v_sub_u32_e32 v57, 0, v56
	v_ldexp_f32 v13, v13, v57
	v_ldexp_f32 v15, v15, v57
	v_add_f32_e32 v57, -1.0, v13
	v_add_f32_e32 v67, 1.0, v13
	v_add_f32_e32 v59, 1.0, v57
	v_add_f32_e32 v69, -1.0, v67
	v_sub_f32_e32 v59, v13, v59
	v_sub_f32_e32 v13, v13, v69
	v_add_f32_e32 v13, v15, v13
	v_add_f32_e32 v59, v15, v59
	v_add_f32_e32 v15, v67, v13
	v_rcp_f32_e32 v69, v15
	v_add_f32_e32 v63, v57, v59
	v_sub_f32_e32 v57, v63, v57
	v_sub_f32_e32 v57, v59, v57
	v_sub_f32_e32 v59, v15, v67
	v_sub_f32_e32 v13, v13, v59
	v_mul_f32_e32 v59, v63, v69
	v_mul_f32_e32 v67, v15, v59
	v_fma_f32 v70, v59, v15, -v67
	v_fmac_f32_e32 v70, v59, v13
	v_add_f32_e32 v71, v67, v70
	v_sub_f32_e32 v72, v63, v71
	v_sub_f32_e32 v63, v63, v72
	v_sub_f32_e32 v67, v71, v67
	v_sub_f32_e32 v63, v63, v71
	v_add_f32_e32 v57, v57, v63
	v_sub_f32_e32 v63, v67, v70
	v_add_f32_e32 v57, v63, v57
	v_add_f32_e32 v63, v72, v57
	v_mul_f32_e32 v67, v69, v63
	v_mul_f32_e32 v70, v15, v67
	v_fma_f32 v15, v67, v15, -v70
	v_fmac_f32_e32 v15, v67, v13
	v_sub_f32_e32 v13, v72, v63
	v_add_f32_e32 v13, v57, v13
	v_add_f32_e32 v57, v70, v15
	v_sub_f32_e32 v71, v63, v57
	v_sub_f32_e32 v63, v63, v71
	v_sub_f32_e32 v70, v57, v70
	v_sub_f32_e32 v57, v63, v57
	v_add_f32_e32 v13, v13, v57
	v_sub_f32_e32 v15, v70, v15
	v_cvt_f32_i32_e32 v56, v56
	v_add_f32_e32 v13, v15, v13
	v_add_f32_e32 v15, v59, v67
	v_add_f32_e32 v13, v71, v13
	v_sub_f32_e32 v57, v15, v59
	v_mul_f32_e32 v13, v69, v13
	v_sub_f32_e32 v57, v67, v57
	v_add_f32_e32 v13, v57, v13
	v_mul_f32_e32 v67, 0x3f317218, v56
	v_add_f32_e32 v57, v15, v13
	v_fma_f32 v69, v56, s10, -v67
	v_mul_f32_e32 v59, v57, v57
	v_fmac_f32_e32 v69, 0xb102e308, v56
	v_sub_f32_e32 v15, v57, v15
	v_fmamk_f32 v63, v59, 0x3e9b6dac, v192
	v_sub_f32_e32 v13, v13, v15
	v_add_f32_e32 v15, v67, v69
	v_fmaak_f32 v63, v59, v63, 0x3f2aaada
	v_sub_f32_e32 v56, v15, v67
	v_ldexp_f32 v67, v57, 1
	v_mul_f32_e32 v57, v57, v59
	v_mul_f32_e32 v57, v57, v63
	v_add_f32_e32 v59, v67, v57
	v_sub_f32_e32 v63, v59, v67
	v_ldexp_f32 v13, v13, 1
	v_sub_f32_e32 v57, v57, v63
	v_add_f32_e32 v13, v13, v57
	v_add_f32_e32 v57, v59, v13
	v_sub_f32_e32 v59, v57, v59
	v_sub_f32_e32 v13, v13, v59
	v_add_f32_e32 v59, v15, v57
	v_sub_f32_e32 v63, v59, v15
	v_sub_f32_e32 v67, v59, v63
	v_sub_f32_e32 v56, v69, v56
	v_sub_f32_e32 v15, v15, v67
	v_sub_f32_e32 v57, v57, v63
	v_add_f32_e32 v15, v57, v15
	v_add_f32_e32 v57, v56, v13
	v_sub_f32_e32 v63, v57, v56
	v_sub_f32_e32 v67, v57, v63
	v_sub_f32_e32 v56, v56, v67
	v_sub_f32_e32 v13, v13, v63
	v_add_f32_e32 v15, v57, v15
	v_add_f32_e32 v13, v13, v56
	v_add_f32_e32 v56, v59, v15
	v_sub_f32_e32 v57, v56, v59
	v_sub_f32_e32 v15, v15, v57
	v_add_f32_e32 v13, v13, v15
	v_add_f32_e32 v13, v56, v13
	v_cmp_neq_f32_e32 vcc, s21, v58
	s_waitcnt vmcnt(0)
	v_mul_f32_e32 v15, 0xbfb8aa3b, v52
	v_exp_f32_e32 v15, v15
	v_cndmask_b32_e32 v13, v199, v13, vcc
	v_cmp_ngt_f32_e32 vcc, -1.0, v58
	s_nop 1
	v_cndmask_b32_e32 v13, v200, v13, vcc
	v_cmp_neq_f32_e32 vcc, -1.0, v58
	s_nop 1
	v_cndmask_b32_e32 v13, v194, v13, vcc
	v_cmp_lt_f32_e64 vcc, |v58|, s11
	s_nop 1
	v_cndmask_b32_e32 v13, v13, v58, vcc
	v_mul_f32_e32 v96, 0x41000000, v13
	v_add_f32_e32 v13, 1.0, v15
	v_add_f32_e32 v52, -1.0, v13
	v_sub_f32_e32 v56, v52, v13
	v_add_f32_e32 v56, 1.0, v56
	v_sub_f32_e32 v52, v15, v52
	v_add_f32_e32 v52, v52, v56
	v_frexp_mant_f32_e32 v58, v13
	v_cvt_f64_f32_e32 v[56:57], v13
	v_frexp_exp_i32_f64_e32 v56, v[56:57]
	v_cmp_gt_f32_e32 vcc, s3, v58
	s_nop 1
	v_subbrev_co_u32_e32 v56, vcc, 0, v56, vcc
	v_sub_u32_e32 v57, 0, v56
	v_ldexp_f32 v13, v13, v57
	v_ldexp_f32 v52, v52, v57
	v_add_f32_e32 v57, -1.0, v13
	v_add_f32_e32 v63, 1.0, v13
	v_add_f32_e32 v58, 1.0, v57
	v_add_f32_e32 v67, -1.0, v63
	v_sub_f32_e32 v58, v13, v58
	v_sub_f32_e32 v13, v13, v67
	v_add_f32_e32 v13, v52, v13
	v_add_f32_e32 v58, v52, v58
	v_add_f32_e32 v52, v63, v13
	v_rcp_f32_e32 v67, v52
	v_add_f32_e32 v59, v57, v58
	v_sub_f32_e32 v57, v59, v57
	v_sub_f32_e32 v57, v58, v57
	v_sub_f32_e32 v58, v52, v63
	v_sub_f32_e32 v13, v13, v58
	v_mul_f32_e32 v58, v59, v67
	v_mul_f32_e32 v63, v52, v58
	v_fma_f32 v69, v58, v52, -v63
	v_fmac_f32_e32 v69, v58, v13
	v_add_f32_e32 v70, v63, v69
	v_sub_f32_e32 v71, v59, v70
	v_sub_f32_e32 v59, v59, v71
	v_sub_f32_e32 v63, v70, v63
	v_sub_f32_e32 v59, v59, v70
	v_add_f32_e32 v57, v57, v59
	v_sub_f32_e32 v59, v63, v69
	v_add_f32_e32 v57, v59, v57
	v_add_f32_e32 v59, v71, v57
	v_mul_f32_e32 v63, v67, v59
	v_mul_f32_e32 v69, v52, v63
	v_fma_f32 v52, v63, v52, -v69
	v_fmac_f32_e32 v52, v63, v13
	v_sub_f32_e32 v13, v71, v59
	v_add_f32_e32 v13, v57, v13
	v_add_f32_e32 v57, v69, v52
	v_sub_f32_e32 v70, v59, v57
	v_sub_f32_e32 v59, v59, v70
	v_sub_f32_e32 v69, v57, v69
	v_sub_f32_e32 v57, v59, v57
	v_add_f32_e32 v13, v13, v57
	v_sub_f32_e32 v52, v69, v52
	v_cvt_f32_i32_e32 v56, v56
	v_add_f32_e32 v13, v52, v13
	v_add_f32_e32 v52, v58, v63
	v_add_f32_e32 v13, v70, v13
	v_sub_f32_e32 v57, v52, v58
	v_mul_f32_e32 v13, v67, v13
	v_sub_f32_e32 v57, v63, v57
	v_add_f32_e32 v13, v57, v13
	v_mul_f32_e32 v63, 0x3f317218, v56
	v_add_f32_e32 v57, v52, v13
	v_fma_f32 v67, v56, s10, -v63
	v_mul_f32_e32 v58, v57, v57
	v_fmac_f32_e32 v67, 0xb102e308, v56
; __device__ __forceinline__ void rglru_unit(const Params& p, const WS& ws, int j, int u, bool dry = false) {
;     ...
;       const int ch = j * 1024 + 128 * g + 32 * jq + 16 * mt + 4 * lq + jj;
;       ba[mt][jj] = p.ab_gate_a_b[ch]; bx[mt][jj] = p.ab_gate_x_b[ch];
;       sp[mt][jj] = 8.f * log1pf(__expf(-p.ab_lam[ch]));
;     }
	v_sub_f32_e32 v52, v57, v52
	v_fmamk_f32 v59, v58, 0x3e9b6dac, v192
	v_sub_f32_e32 v13, v13, v52
	v_add_f32_e32 v52, v63, v67
	v_fmaak_f32 v59, v58, v59, 0x3f2aaada
	v_sub_f32_e32 v56, v52, v63
	v_ldexp_f32 v63, v57, 1
	v_mul_f32_e32 v57, v57, v58
	v_mul_f32_e32 v57, v57, v59
	v_add_f32_e32 v58, v63, v57
	v_sub_f32_e32 v59, v58, v63
	v_ldexp_f32 v13, v13, 1
	v_sub_f32_e32 v57, v57, v59
	v_add_f32_e32 v13, v13, v57
	v_add_f32_e32 v57, v58, v13
	v_sub_f32_e32 v58, v57, v58
	v_sub_f32_e32 v13, v13, v58
	v_add_f32_e32 v58, v52, v57
	v_sub_f32_e32 v59, v58, v52
	v_sub_f32_e32 v63, v58, v59
	v_sub_f32_e32 v56, v67, v56
	v_sub_f32_e32 v52, v52, v63
	v_sub_f32_e32 v57, v57, v59
	v_add_f32_e32 v52, v57, v52
	v_add_f32_e32 v57, v56, v13
	v_sub_f32_e32 v59, v57, v56
	v_sub_f32_e32 v63, v57, v59
	v_sub_f32_e32 v56, v56, v63
	v_sub_f32_e32 v13, v13, v59
	v_add_f32_e32 v52, v57, v52
	v_add_f32_e32 v13, v13, v56
	v_add_f32_e32 v56, v58, v52
	v_sub_f32_e32 v57, v56, v58
	v_sub_f32_e32 v52, v52, v57
	v_add_f32_e32 v13, v13, v52
	v_add_f32_e32 v13, v56, v13
	v_cmp_neq_f32_e32 vcc, s21, v15
	v_mul_f32_e32 v52, 0xbfb8aa3b, v53
	v_exp_f32_e32 v56, v52
	v_cndmask_b32_e32 v13, v199, v13, vcc
	v_cmp_ngt_f32_e32 vcc, -1.0, v15
	v_mov_b32_e32 v71, v12
	s_nop 0
	v_cndmask_b32_e32 v13, v200, v13, vcc
	v_cmp_neq_f32_e32 vcc, -1.0, v15
	s_nop 1
	v_cndmask_b32_e32 v13, v194, v13, vcc
	v_cmp_lt_f32_e64 vcc, |v15|, s11
	s_nop 1
	v_cndmask_b32_e32 v13, v13, v15, vcc
	v_mul_f32_e32 v97, 0x41000000, v13
	v_add_f32_e32 v13, 1.0, v56
	v_add_f32_e32 v15, -1.0, v13
	v_sub_f32_e32 v52, v15, v13
	v_add_f32_e32 v52, 1.0, v52
	v_sub_f32_e32 v15, v56, v15
	v_add_f32_e32 v15, v15, v52
	v_frexp_mant_f32_e32 v57, v13
	v_cvt_f64_f32_e32 v[52:53], v13
	v_frexp_exp_i32_f64_e32 v52, v[52:53]
	v_cmp_gt_f32_e32 vcc, s3, v57
	s_nop 1
	v_subbrev_co_u32_e32 v52, vcc, 0, v52, vcc
	v_sub_u32_e32 v53, 0, v52
	v_ldexp_f32 v13, v13, v53
	v_ldexp_f32 v15, v15, v53
	v_add_f32_e32 v53, -1.0, v13
	v_add_f32_e32 v59, 1.0, v13
	v_add_f32_e32 v57, 1.0, v53
	v_add_f32_e32 v63, -1.0, v59
	v_sub_f32_e32 v57, v13, v57
	v_sub_f32_e32 v13, v13, v63
	v_add_f32_e32 v13, v15, v13
	v_add_f32_e32 v57, v15, v57
	v_add_f32_e32 v15, v59, v13
	v_rcp_f32_e32 v63, v15
	v_add_f32_e32 v58, v53, v57
	v_sub_f32_e32 v53, v58, v53
	v_sub_f32_e32 v53, v57, v53
	v_sub_f32_e32 v57, v15, v59
	v_sub_f32_e32 v13, v13, v57
	v_mul_f32_e32 v57, v58, v63
	v_mul_f32_e32 v59, v15, v57
	v_fma_f32 v67, v57, v15, -v59
	v_fmac_f32_e32 v67, v57, v13
	v_add_f32_e32 v69, v59, v67
	v_sub_f32_e32 v70, v58, v69
	v_sub_f32_e32 v58, v58, v70
	v_sub_f32_e32 v59, v69, v59
	v_sub_f32_e32 v58, v58, v69
	v_add_f32_e32 v53, v53, v58
	v_sub_f32_e32 v58, v59, v67
	v_add_f32_e32 v53, v58, v53
	v_add_f32_e32 v58, v70, v53
	v_mul_f32_e32 v59, v63, v58
	v_mul_f32_e32 v67, v15, v59
	v_fma_f32 v15, v59, v15, -v67
	v_fmac_f32_e32 v15, v59, v13
	v_sub_f32_e32 v13, v70, v58
	v_add_f32_e32 v13, v53, v13
	v_add_f32_e32 v53, v67, v15
	v_sub_f32_e32 v69, v58, v53
	v_sub_f32_e32 v58, v58, v69
	v_sub_f32_e32 v67, v53, v67
	v_sub_f32_e32 v53, v58, v53
	v_add_f32_e32 v13, v13, v53
	v_sub_f32_e32 v15, v67, v15
	v_cvt_f32_i32_e32 v52, v52
	v_add_f32_e32 v13, v15, v13
	v_add_f32_e32 v15, v57, v59
	v_add_f32_e32 v13, v69, v13
	v_sub_f32_e32 v53, v15, v57
	v_mul_f32_e32 v13, v63, v13
	v_sub_f32_e32 v53, v59, v53
	v_add_f32_e32 v13, v53, v13
	v_mul_f32_e32 v59, 0x3f317218, v52
	v_add_f32_e32 v53, v15, v13
	v_fma_f32 v63, v52, s10, -v59
	v_mul_f32_e32 v57, v53, v53
	v_fmac_f32_e32 v63, 0xb102e308, v52
	v_sub_f32_e32 v15, v53, v15
	v_fmamk_f32 v58, v57, 0x3e9b6dac, v192
	v_sub_f32_e32 v13, v13, v15
	v_add_f32_e32 v15, v59, v63
	v_fmaak_f32 v58, v57, v58, 0x3f2aaada
	v_sub_f32_e32 v52, v15, v59
	v_ldexp_f32 v59, v53, 1
	v_mul_f32_e32 v53, v53, v57
	v_mul_f32_e32 v53, v53, v58
	v_add_f32_e32 v57, v59, v53
	v_sub_f32_e32 v58, v57, v59
	v_ldexp_f32 v13, v13, 1
	v_sub_f32_e32 v53, v53, v58
	v_add_f32_e32 v13, v13, v53
	v_add_f32_e32 v53, v57, v13
	v_sub_f32_e32 v57, v53, v57
	v_sub_f32_e32 v13, v13, v57
	v_add_f32_e32 v57, v15, v53
	v_sub_f32_e32 v58, v57, v15
	v_sub_f32_e32 v59, v57, v58
	v_sub_f32_e32 v52, v63, v52
	v_sub_f32_e32 v15, v15, v59
	v_sub_f32_e32 v53, v53, v58
	v_add_f32_e32 v15, v53, v15
	v_add_f32_e32 v53, v52, v13
	v_sub_f32_e32 v58, v53, v52
	v_sub_f32_e32 v59, v53, v58
	v_sub_f32_e32 v52, v52, v59
	v_sub_f32_e32 v13, v13, v58
	v_add_f32_e32 v15, v53, v15
	v_add_f32_e32 v13, v13, v52
	v_add_f32_e32 v52, v57, v15
	v_sub_f32_e32 v53, v52, v57
	v_sub_f32_e32 v15, v15, v53
	v_add_f32_e32 v13, v13, v15
	v_add_f32_e32 v13, v52, v13
	v_cmp_neq_f32_e32 vcc, s21, v56
	v_mul_f32_e32 v15, 0xbfb8aa3b, v54
	v_exp_f32_e32 v15, v15
	v_cndmask_b32_e32 v13, v199, v13, vcc
	v_cmp_ngt_f32_e32 vcc, -1.0, v56
	v_lshlrev_b32_e32 v70, 1, v14
	s_nop 0
	v_cndmask_b32_e32 v13, v200, v13, vcc
	v_cmp_neq_f32_e32 vcc, -1.0, v56
	s_nop 1
	v_cndmask_b32_e32 v13, v194, v13, vcc
	v_cmp_lt_f32_e64 vcc, |v56|, s11
	s_nop 1
	v_cndmask_b32_e32 v13, v13, v56, vcc
	v_mul_f32_e32 v98, 0x41000000, v13
	v_add_f32_e32 v13, 1.0, v15
	v_add_f32_e32 v52, -1.0, v13
	v_sub_f32_e32 v53, v52, v13
	v_add_f32_e32 v53, 1.0, v53
	v_sub_f32_e32 v52, v15, v52
	v_add_f32_e32 v54, v52, v53
	v_frexp_mant_f32_e32 v56, v13
	v_cvt_f64_f32_e32 v[52:53], v13
	v_frexp_exp_i32_f64_e32 v52, v[52:53]
	v_cmp_gt_f32_e32 vcc, s3, v56
	s_nop 1
	v_subbrev_co_u32_e32 v52, vcc, 0, v52, vcc
	v_sub_u32_e32 v53, 0, v52
	v_ldexp_f32 v13, v13, v53
	v_ldexp_f32 v53, v54, v53
	v_add_f32_e32 v54, -1.0, v13
	v_add_f32_e32 v58, 1.0, v13
	v_add_f32_e32 v56, 1.0, v54
	v_add_f32_e32 v59, -1.0, v58
	v_sub_f32_e32 v56, v13, v56
	v_sub_f32_e32 v13, v13, v59
; __device__ __forceinline__ void rglru_unit(const Params& p, const WS& ws, int j, int u, bool dry = false) {
;     ...
;       const int ch = j * 1024 + 128 * g + 32 * jq + 16 * mt + 4 * lq + jj;
;       ba[mt][jj] = p.ab_gate_a_b[ch]; bx[mt][jj] = p.ab_gate_x_b[ch];
;       sp[mt][jj] = 8.f * log1pf(__expf(-p.ab_lam[ch]));
;     }
	v_add_f32_e32 v13, v53, v13
	v_add_f32_e32 v56, v53, v56
	v_add_f32_e32 v53, v58, v13
	v_rcp_f32_e32 v59, v53
	v_add_f32_e32 v57, v54, v56
	v_sub_f32_e32 v54, v57, v54
	v_sub_f32_e32 v54, v56, v54
	v_sub_f32_e32 v56, v53, v58
	v_sub_f32_e32 v13, v13, v56
	v_mul_f32_e32 v56, v57, v59
	v_mul_f32_e32 v58, v53, v56
	v_fma_f32 v63, v56, v53, -v58
	v_fmac_f32_e32 v63, v56, v13
	v_add_f32_e32 v67, v58, v63
	v_sub_f32_e32 v69, v57, v67
	v_sub_f32_e32 v57, v57, v69
	v_sub_f32_e32 v58, v67, v58
	v_sub_f32_e32 v57, v57, v67
	v_add_f32_e32 v54, v54, v57
	v_sub_f32_e32 v57, v58, v63
	v_add_f32_e32 v54, v57, v54
	v_add_f32_e32 v57, v69, v54
	v_mul_f32_e32 v58, v59, v57
	v_mul_f32_e32 v63, v53, v58
	v_fma_f32 v53, v58, v53, -v63
	v_fmac_f32_e32 v53, v58, v13
	v_sub_f32_e32 v13, v69, v57
	v_add_f32_e32 v13, v54, v13
	v_add_f32_e32 v54, v63, v53
	v_sub_f32_e32 v67, v57, v54
	v_sub_f32_e32 v57, v57, v67
	v_sub_f32_e32 v63, v54, v63
	v_sub_f32_e32 v54, v57, v54
	v_add_f32_e32 v13, v13, v54
	v_sub_f32_e32 v53, v63, v53
	v_cvt_f32_i32_e32 v52, v52
	v_add_f32_e32 v13, v53, v13
	v_add_f32_e32 v53, v56, v58
	v_add_f32_e32 v13, v67, v13
	v_sub_f32_e32 v54, v53, v56
	v_mul_f32_e32 v13, v59, v13
	v_sub_f32_e32 v54, v58, v54
	v_add_f32_e32 v13, v54, v13
	v_mul_f32_e32 v58, 0x3f317218, v52
	v_add_f32_e32 v54, v53, v13
	v_fma_f32 v59, v52, s10, -v58
	v_mul_f32_e32 v56, v54, v54
	v_fmac_f32_e32 v59, 0xb102e308, v52
	v_sub_f32_e32 v52, v54, v53
	v_fmamk_f32 v57, v56, 0x3e9b6dac, v192
	v_sub_f32_e32 v13, v13, v52
	v_add_f32_e32 v52, v58, v59
	v_fmaak_f32 v57, v56, v57, 0x3f2aaada
	v_sub_f32_e32 v53, v52, v58
	v_ldexp_f32 v58, v54, 1
	v_mul_f32_e32 v54, v54, v56
	v_mul_f32_e32 v54, v54, v57
	v_add_f32_e32 v56, v58, v54
	v_sub_f32_e32 v57, v56, v58
	v_ldexp_f32 v13, v13, 1
	v_sub_f32_e32 v54, v54, v57
	v_add_f32_e32 v13, v13, v54
	v_add_f32_e32 v54, v56, v13
	v_sub_f32_e32 v56, v54, v56
	v_sub_f32_e32 v13, v13, v56
	v_add_f32_e32 v56, v52, v54
	v_sub_f32_e32 v57, v56, v52
	v_sub_f32_e32 v58, v56, v57
	v_sub_f32_e32 v53, v59, v53
	v_sub_f32_e32 v52, v52, v58
	v_sub_f32_e32 v54, v54, v57
	v_add_f32_e32 v52, v54, v52
	v_add_f32_e32 v54, v53, v13
	v_sub_f32_e32 v57, v54, v53
	v_sub_f32_e32 v58, v54, v57
	v_sub_f32_e32 v53, v53, v58
	v_sub_f32_e32 v13, v13, v57
	v_add_f32_e32 v52, v54, v52
	v_add_f32_e32 v13, v13, v53
	v_add_f32_e32 v53, v56, v52
	v_sub_f32_e32 v54, v53, v56
	v_sub_f32_e32 v52, v52, v54
	v_add_f32_e32 v13, v13, v52
	v_add_f32_e32 v13, v53, v13
	v_cmp_neq_f32_e32 vcc, s21, v15
	v_mul_f32_e32 v52, 0xbfb8aa3b, v55
	v_exp_f32_e32 v54, v52
	v_cndmask_b32_e32 v13, v199, v13, vcc
	v_cmp_ngt_f32_e32 vcc, -1.0, v15
	v_mov_b32_e32 v69, v12
	s_nop 0
	v_cndmask_b32_e32 v13, v200, v13, vcc
	v_cmp_neq_f32_e32 vcc, -1.0, v15
	s_nop 1
	v_cndmask_b32_e32 v13, v194, v13, vcc
	v_cmp_lt_f32_e64 vcc, |v15|, s11
	s_nop 1
	v_cndmask_b32_e32 v13, v13, v15, vcc
	v_mul_f32_e32 v99, 0x41000000, v13
	v_add_f32_e32 v13, 1.0, v54
	v_add_f32_e32 v15, -1.0, v13
	v_sub_f32_e32 v52, v15, v13
	v_add_f32_e32 v52, 1.0, v52
	v_sub_f32_e32 v15, v54, v15
	v_add_f32_e32 v15, v15, v52
	v_frexp_mant_f32_e32 v55, v13
	v_cvt_f64_f32_e32 v[52:53], v13
	v_frexp_exp_i32_f64_e32 v52, v[52:53]
	v_cmp_gt_f32_e32 vcc, s3, v55
	s_nop 1
	v_subbrev_co_u32_e32 v52, vcc, 0, v52, vcc
	v_sub_u32_e32 v53, 0, v52
	v_ldexp_f32 v13, v13, v53
	v_ldexp_f32 v15, v15, v53
	v_add_f32_e32 v53, -1.0, v13
	v_add_f32_e32 v57, 1.0, v13
	v_add_f32_e32 v55, 1.0, v53
	v_add_f32_e32 v58, -1.0, v57
	v_sub_f32_e32 v55, v13, v55
	v_sub_f32_e32 v13, v13, v58
	v_add_f32_e32 v13, v15, v13
	v_add_f32_e32 v55, v15, v55
	v_add_f32_e32 v15, v57, v13
	v_rcp_f32_e32 v58, v15
	v_add_f32_e32 v56, v53, v55
	v_sub_f32_e32 v53, v56, v53
	v_sub_f32_e32 v53, v55, v53
	v_sub_f32_e32 v55, v15, v57
; __device__ __forceinline__ void rglru_unit(const Params& p, const WS& ws, int j, int u, bool dry = false) {
;     ...
;       const int ch = j * 1024 + 128 * g + 32 * jq + 16 * mt + 4 * lq + jj;
;       ba[mt][jj] = p.ab_gate_a_b[ch]; bx[mt][jj] = p.ab_gate_x_b[ch];
;       sp[mt][jj] = 8.f * log1pf(__expf(-p.ab_lam[ch]));
;     }
;   const int sc = tid & 31, ssg = tid >> 5;
;   u32x4 xinA[4], xinB[4];
;   bf16_t gavA[8], gavB[8];
;   auto prefetch = [&](int tile, u32x4 (&xin)[4], bf16_t (&gav)[8]) {
;     const int t0 = 64 * tile;
; #pragma unroll
;     for (int i = 0; i < 4; ++i) {
;       const int ci = tid + 256 * i; const int row = ci >> 4, ch = ci & 15; const int t = t0 + row;
;       xin[i] = (u32x4){0, 0, 0, 0};
;       if (t < T_) xin[i] = *(const u32x4*)(ws.XA + (size_t)(b * T_ + t) * 1024 + 128 * g + 8 * ch);
;     ...
; #pragma unroll
;       for (int ks = 0; ks < 4; ++ks) {
;         const bf16x8 xf = *(const bf16x8*)(XC + (16 * w + lr) * 136 + 32 * ks + 8 * lq);
; #pragma unroll
;         for (int gate = 0; gate < 2; ++gate)
; #pragma unroll
;           for (int mt = 0; mt < 2; ++mt) {
;             const bf16x8 wf = *(const bf16x8*)(WG + (gate * 32 + 16 * mt + lr) * 136 + 32 * ks + 8 * lq);
	v_sub_f32_e32 v13, v13, v55
	v_mul_f32_e32 v55, v56, v58
	v_mul_f32_e32 v57, v15, v55
	v_fma_f32 v59, v55, v15, -v57
	v_fmac_f32_e32 v59, v55, v13
	v_add_f32_e32 v63, v57, v59
	v_sub_f32_e32 v67, v56, v63
	v_sub_f32_e32 v56, v56, v67
	v_sub_f32_e32 v57, v63, v57
	v_sub_f32_e32 v56, v56, v63
	v_add_f32_e32 v53, v53, v56
	v_sub_f32_e32 v56, v57, v59
	v_add_f32_e32 v53, v56, v53
	v_add_f32_e32 v56, v67, v53
	v_mul_f32_e32 v57, v58, v56
	v_mul_f32_e32 v59, v15, v57
	v_fma_f32 v15, v57, v15, -v59
	v_fmac_f32_e32 v15, v57, v13
	v_sub_f32_e32 v13, v67, v56
	v_add_f32_e32 v13, v53, v13
	v_add_f32_e32 v53, v59, v15
	v_sub_f32_e32 v63, v56, v53
	v_sub_f32_e32 v56, v56, v63
	v_sub_f32_e32 v59, v53, v59
	v_sub_f32_e32 v53, v56, v53
	v_add_f32_e32 v13, v13, v53
	v_sub_f32_e32 v15, v59, v15
	v_cvt_f32_i32_e32 v52, v52
	v_add_f32_e32 v13, v15, v13
	v_add_f32_e32 v15, v55, v57
	v_add_f32_e32 v13, v63, v13
	v_sub_f32_e32 v53, v15, v55
	v_mul_f32_e32 v13, v58, v13
	v_sub_f32_e32 v53, v57, v53
	v_add_f32_e32 v13, v53, v13
	v_mul_f32_e32 v57, 0x3f317218, v52
	v_add_f32_e32 v53, v15, v13
	v_fma_f32 v58, v52, s10, -v57
	v_mul_f32_e32 v55, v53, v53
	v_fmac_f32_e32 v58, 0xb102e308, v52
	v_sub_f32_e32 v15, v53, v15
	v_fmamk_f32 v56, v55, 0x3e9b6dac, v192
	v_sub_f32_e32 v13, v13, v15
	v_add_f32_e32 v15, v57, v58
	v_fmaak_f32 v56, v55, v56, 0x3f2aaada
	v_sub_f32_e32 v52, v15, v57
	v_ldexp_f32 v57, v53, 1
	v_mul_f32_e32 v53, v53, v55
	v_mul_f32_e32 v53, v53, v56
	v_add_f32_e32 v55, v57, v53
	v_sub_f32_e32 v56, v55, v57
	v_ldexp_f32 v13, v13, 1
	v_sub_f32_e32 v53, v53, v56
	v_add_f32_e32 v13, v13, v53
	v_add_f32_e32 v53, v55, v13
	v_sub_f32_e32 v55, v53, v55
	v_sub_f32_e32 v13, v13, v55
	v_add_f32_e32 v55, v15, v53
	v_sub_f32_e32 v56, v55, v15
	v_sub_f32_e32 v57, v55, v56
	v_sub_f32_e32 v52, v58, v52
	v_sub_f32_e32 v15, v15, v57
	v_sub_f32_e32 v53, v53, v56
	v_add_f32_e32 v15, v53, v15
	v_add_f32_e32 v53, v52, v13
	v_sub_f32_e32 v56, v53, v52
	v_sub_f32_e32 v57, v53, v56
	v_sub_f32_e32 v52, v52, v57
	v_sub_f32_e32 v13, v13, v56
	v_add_f32_e32 v15, v53, v15
	v_add_f32_e32 v13, v13, v52
	v_add_f32_e32 v52, v55, v15
	v_sub_f32_e32 v53, v52, v55
	v_sub_f32_e32 v15, v15, v53
	v_add_f32_e32 v13, v13, v15
	v_mul_lo_u32 v15, v79, s19
	v_add3_u32 v106, s8, v15, v62
	v_mul_lo_u32 v15, v80, s19
	v_add3_u32 v107, s8, v15, v62
	v_mul_lo_u32 v15, v81, s19
	v_add_f32_e32 v13, v52, v13
	v_cmp_neq_f32_e32 vcc, s21, v54
	v_add3_u32 v109, s8, v15, v62
	v_mul_lo_u32 v15, v82, s19
	v_cndmask_b32_e32 v13, v199, v13, vcc
	v_cmp_ngt_f32_e32 vcc, -1.0, v54
	v_add3_u32 v110, s8, v15, v62
	v_ashrrev_i32_e32 v15, 2, v61
	v_cndmask_b32_e32 v13, v200, v13, vcc
	v_cmp_neq_f32_e32 vcc, -1.0, v54
	v_bfi_b32 v15, -16, v15, v61
	v_mul_lo_u32 v52, v15, s19
	v_cndmask_b32_e32 v13, v194, v13, vcc
	v_cmp_lt_f32_e64 vcc, |v54|, s11
	v_add_u32_e32 v53, s8, v52
	v_lshlrev_b32_e32 v52, 4, v64
	v_cndmask_b32_e32 v13, v13, v54, vcc
	v_mul_f32_e32 v105, 0x41000000, v13
	v_and_b32_e32 v13, 15, v61
	v_add_u32_e32 v111, v53, v52
	v_add_u32_e32 v52, s8, v52
	v_mul_u32_u24_e32 v13, 0x88, v13
	v_mad_u64_u32 v[72:73], s[10:11], v15, s9, v[52:53]
	v_lshl_add_u64 v[14:15], s[54:55], 0, v[70:71]
	v_lshl_add_u32 v112, v13, 1, v52
	v_lshlrev_b32_e32 v13, 1, v65
	s_movk_i32 s9, 0x108
	v_lshl_add_u64 v[14:15], v[14:15], 0, s[92:93]
	v_add3_u32 v113, v53, s92, v13
	v_mad_u64_u32 v[52:53], s[10:11], v66, s9, v[60:61]
	v_lshl_add_u64 v[74:75], v[14:15], 0, v[68:69]
	v_lshl_add_u64 v[14:15], s[4:5], 0, v[70:71]
	v_mov_b32_e32 v63, v12
	v_lshl_add_u32 v114, v52, 2, s8
	v_cmp_lt_i32_e32 vcc, 0, v66
	v_or_b32_e32 v73, 7, v84
	v_lshl_add_u64 v[76:77], v[14:15], 0, v[62:63]
	v_add_u32_e32 v69, v84, v83
	v_add_u32_e32 v71, v82, v84
	s_mov_b32 s4, -1
	s_mov_b32 s101, 0
	s_setprio 2

; __device__ __forceinline__ void rglru_unit(const Params& p, const WS& ws, int j, int u, bool dry = false) {
;     ...
;   auto flush_y = [&]() {
;     if (ypend_t0 >= 0) {
; #pragma unroll
;       for (int i = 0; i < 8; ++i) {
;         const int t = ypend_t0 + 8 * ssg + i;
;         if (t < T_ && !dry) ws.GA[(size_t)(b * T_ + t) * 1024 + 128 * g + 32 * jq + sc] = ypend[i];
;       }
;     }
;     ...
;   flush_y();
.LBB0_1563:
	s_setprio 1
	v_add_u32_e32 v0, s4, v83
	v_cmp_gt_i32_e32 vcc, s15, v0
	s_and_saveexec_b64 s[4:5], vcc
	s_cbranch_execz .LBB0_1571
	v_add_u32_e32 v2, v0, v84
	v_ashrrev_i32_e32 v3, 31, v2
	v_lshlrev_b64 v[2:3], 11, v[2:3]
	v_lshl_add_u64 v[2:3], s[54:55], 0, v[2:3]
	v_mov_b32_e32 v71, v12
	v_lshl_add_u64 v[2:3], v[2:3], 0, v[70:71]
	v_lshl_add_u64 v[2:3], v[2:3], 0, s[92:93]
	v_mov_b32_e32 v69, v12
	v_lshl_add_u64 v[2:3], v[2:3], 0, v[68:69]
	global_store_short v[2:3], v58, off
	s_or_b64 exec, exec, s[4:5]
	v_cmp_gt_i32_e32 vcc, s16, v0
	s_and_saveexec_b64 s[4:5], vcc
	s_cbranch_execnz .LBB0_1572
